# v100 + prep_run preamble (3 copies): pooling lines of rows m0-8..m0+7 touched with dummy-destination loads so the run's first-row window recompute hits in cache
# baseline (speedup 1.0000x reference)
.LBB0_447:
	s_and_b64 vcc, exec, s[0:1]
	s_cbranch_vccz .LBB0_557
	s_movk_i32 s0, 0xff
	v_cmp_lt_i32_e32 vcc, s0, v81
	s_and_saveexec_b64 s[0:1], vcc
	s_xor_b64 s[42:43], exec, s[0:1]
	s_cbranch_execz .LBB0_531
	s_movk_i32 s0, 0x33f
	v_cmp_lt_u32_e32 vcc, s0, v81
	s_and_saveexec_b64 s[0:1], vcc
	s_xor_b64 s[16:17], exec, s[0:1]
	s_cbranch_execz .LBB0_501
	s_movk_i32 s0, 0x7bf
	v_cmp_lt_u32_e32 vcc, s0, v81
	v_readlane_b32 s4, v254, 28
	v_readlane_b32 s0, v255, 7
	v_readlane_b32 s5, v254, 29
	s_add_u32 s2, s4, 0x16f00000
	v_readlane_b32 s1, v255, 8
	s_addc_u32 s3, s5, 0
	s_lshl_b64 s[0:1], s[0:1], 2
	s_add_u32 s0, s4, s0
	s_addc_u32 s1, s5, s1
	s_add_u32 s18, s0, 0x2000
	s_addc_u32 s19, s1, 0
	s_and_saveexec_b64 s[0:1], vcc
	s_xor_b64 s[28:29], exec, s[0:1]
	s_cbranch_execz .LBB0_475
	v_mov_b32_e32 v0, 0xfffff800
	v_mov_b32_e32 v1, -1
	v_mad_u64_u32 v[8:9], s[0:1], v81, 10, v[0:1]
	v_mov_b32_e32 v9, v236
	v_readlane_b32 s4, v255, 11
	v_and_b32_e32 v17, 15, v9
	v_bfe_u32 v19, v9, 4, 2
	v_lshlrev_b32_e32 v21, 2, v17
	v_lshlrev_b32_e32 v12, 6, v19
	v_or_b32_e32 v23, 8, v19
	v_readlane_b32 s5, v255, 12
	v_or_b32_e32 v20, 0x100, v21
	v_min_u32_e32 v0, 9, v23
	v_mov_b64_e32 v[10:11], s[4:5]
	s_movk_i32 s0, 0x1200
	v_or_b32_e32 v22, v12, v21
	v_or_b32_e32 v16, v12, v20
	v_lshlrev_b32_e32 v25, 6, v0
	v_mad_i64_i32 v[10:11], s[0:1], v8, s0, v[10:11]
	v_and_b32_e32 v222, 63, v236
	v_lshlrev_b32_e32 v208, 3, v222
	v_mov_b32_e32 v209, 0
	v_lshl_add_u64 v[206:207], v[10:11], 0, v[208:209]
	s_mov_b32 s98, 0xffff7000
	s_mov_b32 s99, -1
	v_lshl_add_u64 v[206:207], v[206:207], 0, s[98:99]
	s_movk_i32 s98, 0x1200
	s_mov_b32 s99, 0
	s_nop 0
	global_load_dwordx2 v[210:211], v[206:207], off
	v_lshl_add_u64 v[206:207], v[206:207], 0, s[98:99]
	s_nop 0
	global_load_dwordx2 v[212:213], v[206:207], off
	v_lshl_add_u64 v[206:207], v[206:207], 0, s[98:99]
	s_nop 0
	global_load_dwordx2 v[214:215], v[206:207], off
	v_lshl_add_u64 v[206:207], v[206:207], 0, s[98:99]
	s_nop 0
	global_load_dwordx2 v[216:217], v[206:207], off
	v_lshl_add_u64 v[206:207], v[206:207], 0, s[98:99]
	s_nop 0
	global_load_dwordx2 v[218:219], v[206:207], off
	v_lshl_add_u64 v[206:207], v[206:207], 0, s[98:99]
	s_nop 0
	global_load_dwordx2 v[220:221], v[206:207], off
	v_lshl_add_u64 v[206:207], v[206:207], 0, s[98:99]
	s_nop 0
	global_load_dwordx2 v[230:231], v[206:207], off
	v_lshl_add_u64 v[206:207], v[206:207], 0, s[98:99]
	s_nop 0
	global_load_dwordx2 v[232:233], v[206:207], off
	v_lshl_add_u64 v[206:207], v[206:207], 0, s[98:99]
	s_nop 0
	global_load_dwordx2 v[234:235], v[206:207], off
	v_lshl_add_u64 v[206:207], v[206:207], 0, s[98:99]
	s_nop 0
	global_load_dwordx2 v[240:241], v[206:207], off
	v_lshl_add_u64 v[206:207], v[206:207], 0, s[98:99]
	s_nop 0
	global_load_dwordx2 v[242:243], v[206:207], off
	v_lshl_add_u64 v[206:207], v[206:207], 0, s[98:99]
	s_nop 0
	global_load_dwordx2 v[248:249], v[206:207], off
	v_lshl_add_u64 v[206:207], v[206:207], 0, s[98:99]
	s_nop 0
	global_load_dwordx2 v[250:251], v[206:207], off
	v_lshl_add_u64 v[206:207], v[206:207], 0, s[98:99]
	s_nop 0
	global_load_dwordx2 v[196:197], v[206:207], off
	v_lshl_add_u64 v[206:207], v[206:207], 0, s[98:99]
	s_nop 0
	global_load_dwordx2 v[198:199], v[206:207], off
	v_lshl_add_u64 v[206:207], v[206:207], 0, s[98:99]
	s_nop 0
	global_load_dwordx2 v[200:201], v[206:207], off
	v_lshl_add_u64 v[206:207], v[206:207], 0, s[98:99]
	v_lshlrev_b32_e32 v160, 1, v22
	v_lshl_add_u64 v[12:13], v[10:11], 0, v[160:161]
	v_lshlrev_b32_e32 v160, 1, v16
	v_or_b32_e32 v24, v25, v21
	v_lshlrev_b32_e32 v4, 4, v17
	v_lshl_add_u64 v[14:15], v[10:11], 0, v[160:161]
	v_lshlrev_b32_e32 v160, 1, v24
	global_load_dwordx4 v[0:3], v4, s[18:19]
	s_nop 0
	global_load_dwordx4 v[4:7], v4, s[18:19] offset:1024
	v_lshl_add_u64 v[10:11], v[10:11], 0, v[160:161]
	global_load_dwordx2 v[46:47], v[12:13], off offset:512
	global_load_dwordx2 v[44:45], v[14:15], off offset:512
	global_load_dwordx2 v[38:39], v[10:11], off offset:512
	v_and_b32_e32 v10, 63, v9
	v_and_b32_e32 v9, 4, v9
	v_cmp_eq_u32_e64 s[36:37], 0, v9
	v_and_b32_e32 v9, 12, v21
	v_cvt_f32_ubyte0_e32 v14, v9
	v_mul_f32_e32 v14, 0xbf549a78, v14
	v_exp_f32_e32 v59, v14
	v_or_b32_e32 v14, 1, v9
	v_cvt_f32_ubyte0_e32 v14, v14
	v_mul_f32_e32 v14, 0xbf549a78, v14
	v_exp_f32_e32 v60, v14
	v_or_b32_e32 v14, 2, v9
	v_or_b32_e32 v9, 3, v9
	v_cvt_f32_ubyte0_e32 v14, v14
	v_cvt_f32_ubyte0_e32 v9, v9
	v_mul_f32_e32 v14, 0xbf549a78, v14
	v_mul_f32_e32 v9, 0xbf549a78, v9
	v_exp_f32_e32 v61, v14
	v_exp_f32_e32 v62, v9
	v_readlane_b32 s0, v254, 28
	v_add_u32_e32 v18, 0x100, v16
	v_or_b32_e32 v20, v25, v20
	v_mov_b32_e32 v64, 0
	v_lshlrev_b32_e32 v160, 3, v10
	v_readlane_b32 s1, v254, 29
	v_cmp_gt_u32_e32 vcc, 10, v23
	v_lshlrev_b32_e64 v58, v19, 1
	v_lshl_add_u64 v[10:11], s[4:5], 0, v[160:161]
	v_cmp_gt_u32_e64 s[38:39], 8, v17
	v_lshl_add_u64 v[12:13], s[2:3], 0, v[160:161]
	v_lshl_add_u64 v[14:15], s[0:1], 0, v[160:161]
	s_mov_b32 s14, 0
	v_lshlrev_b32_e32 v16, 1, v16
	v_lshlrev_b32_e32 v18, 1, v18
	v_lshlrev_b32_e32 v20, 1, v20
	v_lshlrev_b32_e32 v22, 1, v22
	v_lshlrev_b32_e32 v24, 1, v24
	v_mov_b32_e32 v63, v8
	v_mov_b32_e32 v23, 0
	v_mov_b32_e32 v40, 0
	v_mov_b32_e32 v41, v64
	v_mov_b32_e32 v42, 0
	v_mov_b32_e32 v43, v64
	s_branch .LBB0_453

.LBB0_475:
	s_andn2_saveexec_b64 s[28:29], s[28:29]
	s_cbranch_execz .LBB0_500
	v_mov_b32_e32 v0, 0xfffff040
	v_mov_b32_e32 v1, -1
	v_mad_u64_u32 v[8:9], s[0:1], v81, 11, v[0:1]
	v_mov_b32_e32 v9, v236
	v_readlane_b32 s4, v255, 11
	v_and_b32_e32 v17, 15, v9
	v_bfe_u32 v19, v9, 4, 2
	v_lshlrev_b32_e32 v21, 2, v17
	v_lshlrev_b32_e32 v12, 6, v19
	v_or_b32_e32 v23, 8, v19
	v_readlane_b32 s5, v255, 12
	v_or_b32_e32 v20, 0x100, v21
	v_min_u32_e32 v0, 9, v23
	v_mov_b64_e32 v[10:11], s[4:5]
	s_movk_i32 s0, 0x1200
	v_or_b32_e32 v22, v12, v21
	v_or_b32_e32 v16, v12, v20
	v_lshlrev_b32_e32 v25, 6, v0
	v_mad_u64_u32 v[10:11], s[0:1], v8, s0, v[10:11]
	v_and_b32_e32 v222, 63, v236
	v_lshlrev_b32_e32 v208, 3, v222
	v_mov_b32_e32 v209, 0
	v_lshl_add_u64 v[206:207], v[10:11], 0, v[208:209]
	s_mov_b32 s98, 0xffff7000
	s_mov_b32 s99, -1
	v_lshl_add_u64 v[206:207], v[206:207], 0, s[98:99]
	s_movk_i32 s98, 0x1200
	s_mov_b32 s99, 0
	s_nop 0
	global_load_dwordx2 v[210:211], v[206:207], off
	v_lshl_add_u64 v[206:207], v[206:207], 0, s[98:99]
	s_nop 0
	global_load_dwordx2 v[212:213], v[206:207], off
	v_lshl_add_u64 v[206:207], v[206:207], 0, s[98:99]
	s_nop 0
	global_load_dwordx2 v[214:215], v[206:207], off
	v_lshl_add_u64 v[206:207], v[206:207], 0, s[98:99]
	s_nop 0
	global_load_dwordx2 v[216:217], v[206:207], off
	v_lshl_add_u64 v[206:207], v[206:207], 0, s[98:99]
	s_nop 0
	global_load_dwordx2 v[218:219], v[206:207], off
	v_lshl_add_u64 v[206:207], v[206:207], 0, s[98:99]
	s_nop 0
	global_load_dwordx2 v[220:221], v[206:207], off
	v_lshl_add_u64 v[206:207], v[206:207], 0, s[98:99]
	s_nop 0
	global_load_dwordx2 v[230:231], v[206:207], off
	v_lshl_add_u64 v[206:207], v[206:207], 0, s[98:99]
	s_nop 0
	global_load_dwordx2 v[232:233], v[206:207], off
	v_lshl_add_u64 v[206:207], v[206:207], 0, s[98:99]
	s_nop 0
	global_load_dwordx2 v[234:235], v[206:207], off
	v_lshl_add_u64 v[206:207], v[206:207], 0, s[98:99]
	s_nop 0
	global_load_dwordx2 v[240:241], v[206:207], off
	v_lshl_add_u64 v[206:207], v[206:207], 0, s[98:99]
	s_nop 0
	global_load_dwordx2 v[242:243], v[206:207], off
	v_lshl_add_u64 v[206:207], v[206:207], 0, s[98:99]
	s_nop 0
	global_load_dwordx2 v[248:249], v[206:207], off
	v_lshl_add_u64 v[206:207], v[206:207], 0, s[98:99]
	s_nop 0
	global_load_dwordx2 v[250:251], v[206:207], off
	v_lshl_add_u64 v[206:207], v[206:207], 0, s[98:99]
	s_nop 0
	global_load_dwordx2 v[196:197], v[206:207], off
	v_lshl_add_u64 v[206:207], v[206:207], 0, s[98:99]
	s_nop 0
	global_load_dwordx2 v[198:199], v[206:207], off
	v_lshl_add_u64 v[206:207], v[206:207], 0, s[98:99]
	s_nop 0
	global_load_dwordx2 v[200:201], v[206:207], off
	v_lshl_add_u64 v[206:207], v[206:207], 0, s[98:99]
	v_lshlrev_b32_e32 v160, 1, v22
	v_lshl_add_u64 v[12:13], v[10:11], 0, v[160:161]
	v_lshlrev_b32_e32 v160, 1, v16
	v_or_b32_e32 v24, v25, v21
	v_lshlrev_b32_e32 v4, 4, v17
	v_lshl_add_u64 v[14:15], v[10:11], 0, v[160:161]
	v_lshlrev_b32_e32 v160, 1, v24
	global_load_dwordx4 v[0:3], v4, s[18:19]
	s_nop 0
	global_load_dwordx4 v[4:7], v4, s[18:19] offset:1024
	v_lshl_add_u64 v[10:11], v[10:11], 0, v[160:161]
	global_load_dwordx2 v[46:47], v[12:13], off offset:512
	global_load_dwordx2 v[44:45], v[14:15], off offset:512
	global_load_dwordx2 v[38:39], v[10:11], off offset:512
	v_and_b32_e32 v10, 63, v9
	v_and_b32_e32 v9, 4, v9
	v_cmp_eq_u32_e64 s[36:37], 0, v9
	v_and_b32_e32 v9, 12, v21
	v_cvt_f32_ubyte0_e32 v14, v9
	v_mul_f32_e32 v14, 0xbf549a78, v14
	v_exp_f32_e32 v59, v14
	v_or_b32_e32 v14, 1, v9
	v_cvt_f32_ubyte0_e32 v14, v14
	v_mul_f32_e32 v14, 0xbf549a78, v14
	v_exp_f32_e32 v60, v14
	v_or_b32_e32 v14, 2, v9
	v_or_b32_e32 v9, 3, v9
	v_cvt_f32_ubyte0_e32 v14, v14
	v_cvt_f32_ubyte0_e32 v9, v9
	v_mul_f32_e32 v14, 0xbf549a78, v14
	v_mul_f32_e32 v9, 0xbf549a78, v9
	v_exp_f32_e32 v61, v14
	v_exp_f32_e32 v62, v9
	v_readlane_b32 s0, v254, 28
	v_add_u32_e32 v18, 0x100, v16
	v_or_b32_e32 v20, v25, v20
	v_mov_b32_e32 v64, 0
	v_lshlrev_b32_e32 v160, 3, v10
	v_readlane_b32 s1, v254, 29
	v_cmp_gt_u32_e32 vcc, 10, v23
	v_lshlrev_b32_e64 v58, v19, 1
	v_lshl_add_u64 v[10:11], s[4:5], 0, v[160:161]
	v_cmp_gt_u32_e64 s[38:39], 8, v17
	v_lshl_add_u64 v[12:13], s[2:3], 0, v[160:161]
	v_lshl_add_u64 v[14:15], s[0:1], 0, v[160:161]
	s_mov_b32 s10, 0
	v_lshlrev_b32_e32 v16, 1, v16
	v_lshlrev_b32_e32 v18, 1, v18
	v_lshlrev_b32_e32 v20, 1, v20
	v_lshlrev_b32_e32 v22, 1, v22
	v_lshlrev_b32_e32 v24, 1, v24
	v_mov_b32_e32 v63, v8
	v_mov_b32_e32 v23, 0
	v_mov_b32_e32 v40, 0
	v_mov_b32_e32 v41, v64
	v_mov_b32_e32 v42, 0
	v_mov_b32_e32 v43, v64
	s_branch .LBB0_478

.LBB0_531:
	s_andn2_saveexec_b64 s[2:3], s[42:43]
	s_cbranch_execz .LBB0_556
	v_readlane_b32 s0, v255, 7
	v_mov_b32_e32 v9, v236
	v_readlane_b32 s1, v255, 8
	s_lshl_b64 s[0:1], s[0:1], 2
	v_bfe_u32 v19, v9, 4, 2
	v_readlane_b32 s4, v254, 28
	v_and_b32_e32 v17, 15, v9
	v_or_b32_e32 v23, 8, v19
	v_readlane_b32 s5, v254, 29
	s_add_u32 s0, s4, s0
	v_min_u32_e32 v0, 9, v23
	s_addc_u32 s1, s5, s1
	v_lshlrev_b32_e32 v160, 4, v17
	v_readlane_b32 s6, v255, 11
	v_lshlrev_b32_e32 v21, 2, v17
	v_lshlrev_b32_e32 v12, 6, v19
	v_lshlrev_b32_e32 v24, 6, v0
	v_lshl_add_u64 v[0:1], s[0:1], 0, v[160:161]
	s_mov_b64 s[0:1], 0x2000
	v_readlane_b32 s7, v255, 12
	v_lshlrev_b32_e32 v56, 1, v81
	v_or_b32_e32 v18, 0x100, v21
	v_lshl_add_u64 v[4:5], v[0:1], 0, s[0:1]
	v_mov_b64_e32 v[10:11], s[6:7]
	s_movk_i32 s0, 0x1200
	v_or_b32_e32 v20, v12, v21
	v_or_b32_e32 v8, v12, v18
	v_mad_i64_i32 v[10:11], s[0:1], v56, s0, v[10:11]
	v_and_b32_e32 v222, 63, v236
	v_lshlrev_b32_e32 v208, 3, v222
	v_mov_b32_e32 v209, 0
	v_lshl_add_u64 v[206:207], v[10:11], 0, v[208:209]
	s_mov_b32 s98, 0xffff7000
	s_mov_b32 s99, -1
	v_lshl_add_u64 v[206:207], v[206:207], 0, s[98:99]
	s_movk_i32 s98, 0x1200
	s_mov_b32 s99, 0
	s_nop 0
	global_load_dwordx2 v[210:211], v[206:207], off
	v_lshl_add_u64 v[206:207], v[206:207], 0, s[98:99]
	s_nop 0
	global_load_dwordx2 v[212:213], v[206:207], off
	v_lshl_add_u64 v[206:207], v[206:207], 0, s[98:99]
	s_nop 0
	global_load_dwordx2 v[214:215], v[206:207], off
	v_lshl_add_u64 v[206:207], v[206:207], 0, s[98:99]
	s_nop 0
	global_load_dwordx2 v[216:217], v[206:207], off
	v_lshl_add_u64 v[206:207], v[206:207], 0, s[98:99]
	s_nop 0
	global_load_dwordx2 v[218:219], v[206:207], off
	v_lshl_add_u64 v[206:207], v[206:207], 0, s[98:99]
	s_nop 0
	global_load_dwordx2 v[220:221], v[206:207], off
	v_lshl_add_u64 v[206:207], v[206:207], 0, s[98:99]
	s_nop 0
	global_load_dwordx2 v[230:231], v[206:207], off
	v_lshl_add_u64 v[206:207], v[206:207], 0, s[98:99]
	s_nop 0
	global_load_dwordx2 v[232:233], v[206:207], off
	v_lshl_add_u64 v[206:207], v[206:207], 0, s[98:99]
	s_nop 0
	global_load_dwordx2 v[234:235], v[206:207], off
	v_lshl_add_u64 v[206:207], v[206:207], 0, s[98:99]
	s_nop 0
	global_load_dwordx2 v[240:241], v[206:207], off
	v_lshl_add_u64 v[206:207], v[206:207], 0, s[98:99]
	s_nop 0
	global_load_dwordx2 v[242:243], v[206:207], off
	v_lshl_add_u64 v[206:207], v[206:207], 0, s[98:99]
	s_nop 0
	global_load_dwordx2 v[248:249], v[206:207], off
	v_lshl_add_u64 v[206:207], v[206:207], 0, s[98:99]
	s_nop 0
	global_load_dwordx2 v[250:251], v[206:207], off
	v_lshl_add_u64 v[206:207], v[206:207], 0, s[98:99]
	s_nop 0
	global_load_dwordx2 v[196:197], v[206:207], off
	v_lshl_add_u64 v[206:207], v[206:207], 0, s[98:99]
	s_nop 0
	global_load_dwordx2 v[198:199], v[206:207], off
	v_lshl_add_u64 v[206:207], v[206:207], 0, s[98:99]
	s_nop 0
	global_load_dwordx2 v[200:201], v[206:207], off
	v_lshl_add_u64 v[206:207], v[206:207], 0, s[98:99]
	v_lshlrev_b32_e32 v160, 1, v20
	v_add_co_u32_e32 v0, vcc, s20, v0
	v_lshl_add_u64 v[12:13], v[10:11], 0, v[160:161]
	v_lshlrev_b32_e32 v160, 1, v8
	v_or_b32_e32 v22, v24, v21
	v_addc_co_u32_e32 v1, vcc, 0, v1, vcc
	v_lshl_add_u64 v[14:15], v[10:11], 0, v[160:161]
	v_lshlrev_b32_e32 v160, 1, v22
	global_load_dwordx4 v[0:3], v[0:1], off
	s_nop 0
	global_load_dwordx4 v[4:7], v[4:5], off offset:1024
	v_lshl_add_u64 v[10:11], v[10:11], 0, v[160:161]
	global_load_dwordx2 v[44:45], v[12:13], off offset:512
	global_load_dwordx2 v[42:43], v[14:15], off offset:512
	global_load_dwordx2 v[36:37], v[10:11], off offset:512
	v_and_b32_e32 v10, 63, v9
	v_and_b32_e32 v9, 4, v9
	v_cmp_eq_u32_e64 s[36:37], 0, v9
	v_and_b32_e32 v9, 12, v21
	v_cmp_gt_u32_e64 s[38:39], 8, v17
	v_cvt_f32_ubyte0_e32 v17, v9
	v_mul_f32_e32 v17, 0xbf549a78, v17
	v_exp_f32_e32 v58, v17
	v_or_b32_e32 v17, 1, v9
	v_cvt_f32_ubyte0_e32 v17, v17
	v_mul_f32_e32 v17, 0xbf549a78, v17
	v_exp_f32_e32 v59, v17
	v_or_b32_e32 v17, 2, v9
	v_or_b32_e32 v9, 3, v9
	v_cvt_f32_ubyte0_e32 v17, v17
	v_cvt_f32_ubyte0_e32 v9, v9
	v_mul_f32_e32 v17, 0xbf549a78, v17
	v_mul_f32_e32 v9, 0xbf549a78, v9
	v_exp_f32_e32 v60, v17
	v_exp_f32_e32 v61, v9
	v_lshlrev_b32_e32 v160, 3, v10
	v_add_u32_e32 v16, 0x100, v8
	v_or_b32_e32 v18, v24, v18
	v_mov_b32_e32 v63, 0
	v_lshl_add_u64 v[12:13], s[4:5], 0, v[160:161]
	s_mov_b64 s[0:1], 0x16f00000
	v_cmp_gt_u32_e32 vcc, 10, v23
	v_lshlrev_b32_e64 v57, v19, 1
	v_lshl_add_u64 v[10:11], s[6:7], 0, v[160:161]
	v_lshl_add_u64 v[14:15], v[12:13], 0, s[0:1]
	s_mov_b32 s14, 0
	v_lshlrev_b32_e32 v8, 1, v8
	v_lshlrev_b32_e32 v16, 1, v16
	v_lshlrev_b32_e32 v18, 1, v18
	v_lshlrev_b32_e32 v20, 1, v20
	v_lshlrev_b32_e32 v22, 1, v22
	v_mov_b32_e32 v62, v56
	v_mov_b32_e32 v21, 0
	v_mov_b32_e32 v38, 0
	v_mov_b32_e32 v39, v63
	v_mov_b32_e32 v40, 0
	v_mov_b32_e32 v41, v63
	s_branch .LBB0_534
